# v113 + s_setprio 1/0 around the phase-2/3 HGRN MFMA clusters
# baseline (speedup 1.0000x reference)
.LBB0_301:
	s_or_b64 exec, exec, s[8:9]
	s_waitcnt lgkmcnt(0)
	s_barrier
	ds_read_b128 v[82:85], v74 offset:96
	ds_read_b128 v[86:89], v74 offset:64
	ds_read_b128 v[90:93], v74 offset:32
	ds_read_b128 v[94:97], v74
	ds_read_b128 v[98:101], v81 offset:34816
	s_waitcnt lgkmcnt(4)
	v_pk_mul_f32 v[14:15], v[14:15], v[84:85]
	v_pk_mul_f32 v[12:13], v[12:13], v[82:83]
	ds_read_b128 v[82:85], v80 offset:53248
	s_waitcnt lgkmcnt(4)
	v_pk_mul_f32 v[10:11], v[10:11], v[88:89]
	s_waitcnt lgkmcnt(3)
	v_pk_mul_f32 v[6:7], v[6:7], v[92:93]
	s_waitcnt lgkmcnt(2)
	v_pk_mul_f32 v[2:3], v[2:3], v[96:97]
	v_pk_mul_f32 v[8:9], v[8:9], v[86:87]
	v_pk_mul_f32 v[4:5], v[4:5], v[90:91]
	v_pk_mul_f32 v[0:1], v[0:1], v[94:95]
	ds_read_b128 v[86:89], v80 offset:53280
	ds_read_b128 v[90:93], v81 offset:34848
	s_waitcnt lgkmcnt(2)
	v_mfma_f32_32x32x16_bf16 v[0:15], v[98:101], v[82:85], v[0:15]
	s_add_u32 s6, s6, 0x4000
	v_add_f32_e32 v68, v68, v69
	s_addc_u32 s7, s7, 0
	v_add_f32_e32 v70, v70, v68
	s_cmp_eq_u32 s6, 0x20000
	s_waitcnt lgkmcnt(0)
	v_mfma_f32_32x32x16_bf16 v[0:15], v[90:93], v[86:89], v[0:15]
	ds_read_b128 v[90:93], v81 offset:34880
	ds_read_b128 v[94:97], v80 offset:53312
	ds_read_b128 v[98:101], v80 offset:53344
	ds_read_b128 v[102:105], v81 offset:34912
	s_waitcnt lgkmcnt(2)
	v_mfma_f32_32x32x16_bf16 v[0:15], v[90:93], v[94:97], v[0:15]
	ds_read_b128 v[90:93], v74 offset:224
	ds_read_b128 v[106:109], v74 offset:192
	ds_read_b128 v[110:113], v74 offset:128
	ds_read_b128 v[114:117], v74 offset:160
	ds_read_b128 v[118:121], v81 offset:39424
	s_waitcnt lgkmcnt(4)
	v_pk_mul_f32 v[62:63], v[62:63], v[92:93]
	s_waitcnt lgkmcnt(3)
	v_pk_mul_f32 v[58:59], v[58:59], v[108:109]
	s_waitcnt lgkmcnt(2)
	v_pk_mul_f32 v[50:51], v[50:51], v[112:113]
	s_waitcnt lgkmcnt(1)
	v_pk_mul_f32 v[54:55], v[54:55], v[116:117]
	v_pk_mul_f32 v[60:61], v[60:61], v[90:91]
	v_pk_mul_f32 v[56:57], v[56:57], v[106:107]
	v_pk_mul_f32 v[52:53], v[52:53], v[114:115]
	v_pk_mul_f32 v[48:49], v[48:49], v[110:111]
	ds_read_b128 v[90:93], v81 offset:39456
	s_setprio 1
	v_mfma_f32_32x32x16_bf16 v[0:15], v[102:105], v[98:101], v[0:15]
	ds_read_b128 v[102:105], v74 offset:320
	ds_read_b128 v[106:109], v74 offset:352
	ds_read_b128 v[110:113], v81 offset:39488
	s_waitcnt lgkmcnt(2)
	v_mul_f32_e64 v42, v42, v104
	v_mul_f32_e64 v43, v43, v105
	s_waitcnt lgkmcnt(1)
	v_pk_mul_f32 v[46:47], v[46:47], v[108:109]
	v_pk_mul_f32 v[44:45], v[44:45], v[106:107]
	v_pk_mul_f32 v[40:41], v[40:41], v[102:103]
	v_mfma_f32_32x32x16_bf16 v[48:63], v[118:121], v[82:85], v[48:63]
	v_mfma_f32_32x32x16_bf16 v[48:63], v[90:93], v[86:89], v[48:63]
	ds_read_b128 v[90:93], v74 offset:256
	ds_read_b128 v[114:117], v74 offset:288
	ds_read_b128 v[118:121], v81 offset:39520
	s_waitcnt lgkmcnt(2)
	v_mul_f32_e64 v34, v34, v92
	v_mul_f32_e64 v35, v35, v93
	s_waitcnt lgkmcnt(1)
	v_pk_mul_f32 v[38:39], v[38:39], v[116:117]
	v_pk_mul_f32 v[36:37], v[36:37], v[114:115]
	v_mfma_f32_32x32x16_bf16 v[48:63], v[110:113], v[94:97], v[48:63]
	ds_read_b128 v[102:105], v74 offset:448
	ds_read_b128 v[106:109], v74 offset:480
	ds_read_b128 v[110:113], v81 offset:44032
	v_mul_f32_e64 v32, v32, v90
	v_mul_f32_e64 v33, v33, v91
	s_waitcnt lgkmcnt(2)
	v_pk_mul_f32 v[26:27], v[26:27], v[104:105]
	s_waitcnt lgkmcnt(1)
	v_pk_mul_f32 v[30:31], v[30:31], v[108:109]
	v_pk_mul_f32 v[28:29], v[28:29], v[106:107]
	v_pk_mul_f32 v[24:25], v[24:25], v[102:103]
	v_mfma_f32_32x32x16_bf16 v[48:63], v[118:121], v[98:101], v[48:63]
	ds_read_b128 v[116:119], v74 offset:384
	ds_read_b128 v[120:123], v74 offset:416
	ds_read_b128 v[90:93], v81 offset:44064
	ds_read_b128 v[102:105], v81 offset:44096
	ds_read_b128 v[106:109], v81 offset:44128
	s_waitcnt lgkmcnt(4)
	v_pk_mul_f32 v[18:19], v[18:19], v[118:119]
	s_waitcnt lgkmcnt(3)
	v_pk_mul_f32 v[22:23], v[22:23], v[122:123]
	v_pk_mul_f32 v[20:21], v[20:21], v[120:121]
	v_mfma_f32_32x32x16_bf16 v[32:47], v[110:113], v[82:85], v[32:47]
	v_mul_f32_e64 v16, v16, v116
	v_mul_f32_e64 v17, v17, v117
	s_waitcnt lgkmcnt(2)
	v_mfma_f32_32x32x16_bf16 v[32:47], v[90:93], v[86:89], v[32:47]
	s_setprio 0
	ds_read_b128 v[90:93], v75
	ds_read_b128 v[110:113], v81 offset:48640
	ds_read_b128 v[114:117], v81 offset:48672
	ds_read_b128 v[118:121], v81 offset:48704
	ds_read_b128 v[122:125], v81 offset:48736
	ds_read_b128 v[126:129], v75 offset:32
	s_waitcnt lgkmcnt(5)
	v_pk_mul_f32 v[0:1], v[0:1], v[90:91]
	v_pk_mul_f32 v[2:3], v[2:3], v[92:93]
	ds_read_b128 v[90:93], v75 offset:96
	s_waitcnt lgkmcnt(1)
	v_pk_mul_f32 v[4:5], v[4:5], v[126:127]
	v_pk_mul_f32 v[6:7], v[6:7], v[128:129]
	s_setprio 1
	v_mfma_f32_32x32x16_bf16 v[16:31], v[110:113], v[82:85], v[16:31]
	ds_read_b128 v[126:129], v75 offset:128
	s_waitcnt lgkmcnt(1)
	v_mul_f32_e64 v12, v12, v90
	v_mul_f32_e64 v13, v13, v91
	v_mul_f32_e64 v14, v14, v92
	v_mul_f32_e64 v15, v15, v93
	ds_read_b128 v[90:93], v75 offset:160
	ds_read_b128 v[82:85], v75 offset:224
	s_waitcnt lgkmcnt(2)
	v_pk_mul_f32 v[48:49], v[48:49], v[126:127]
	v_pk_mul_f32 v[50:51], v[50:51], v[128:129]
	v_mfma_f32_32x32x16_bf16 v[16:31], v[114:117], v[86:89], v[16:31]
	s_waitcnt lgkmcnt(1)
	v_mul_f32_e64 v52, v52, v90
	v_mul_f32_e64 v53, v53, v91
	v_mul_f32_e64 v54, v54, v92
	v_mul_f32_e64 v55, v55, v93
	ds_read_b128 v[90:93], v75 offset:256
	ds_read_b128 v[86:89], v75 offset:288
	s_waitcnt lgkmcnt(2)
	v_pk_mul_f32 v[60:61], v[60:61], v[82:83]
	v_pk_mul_f32 v[62:63], v[62:63], v[84:85]
	ds_read_b128 v[82:85], v75 offset:320
	v_mfma_f32_32x32x16_bf16 v[32:47], v[102:105], v[94:97], v[32:47]
	ds_read_b128 v[102:105], v75 offset:64
	s_waitcnt lgkmcnt(0)
	v_mul_f32_e64 v8, v8, v102
	v_mul_f32_e64 v9, v9, v103
	v_mul_f32_e64 v10, v10, v104
	v_mul_f32_e64 v11, v11, v105
	v_mfma_f32_32x32x16_bf16 v[16:31], v[118:121], v[94:97], v[16:31]
	ds_read_b128 v[102:105], v75 offset:192
	s_waitcnt lgkmcnt(0)
	v_mul_f32_e64 v56, v56, v102
	v_mul_f32_e64 v57, v57, v103
	v_mul_f32_e64 v58, v58, v104
	v_mul_f32_e64 v59, v59, v105
	v_mfma_f32_32x32x16_bf16 v[32:47], v[106:109], v[98:101], v[32:47]
	v_mfma_f32_32x32x16_bf16 v[16:31], v[122:125], v[98:101], v[16:31]
	s_setprio 0
	s_nop 10
	v_mul_f32_e64 v32, v32, v90
	v_mul_f32_e64 v33, v33, v91
	v_mul_f32_e64 v34, v34, v92
	v_mul_f32_e64 v35, v35, v93
	ds_read_b128 v[90:93], v75 offset:352
	v_pk_mul_f32 v[36:37], v[36:37], v[86:87]
	v_pk_mul_f32 v[38:39], v[38:39], v[88:89]
	v_pk_mul_f32 v[40:41], v[40:41], v[82:83]
	v_pk_mul_f32 v[42:43], v[42:43], v[84:85]
	ds_read_b128 v[82:85], v75 offset:384
	ds_read_b128 v[86:89], v75 offset:416
	s_waitcnt lgkmcnt(2)
	v_pk_mul_f32 v[44:45], v[44:45], v[90:91]
	v_pk_mul_f32 v[46:47], v[46:47], v[92:93]
	ds_read_b128 v[90:93], v75 offset:448
	s_waitcnt lgkmcnt(2)
	v_pk_mul_f32 v[16:17], v[16:17], v[82:83]
	v_pk_mul_f32 v[18:19], v[18:19], v[84:85]
	ds_read_b128 v[82:85], v75 offset:480
	s_waitcnt lgkmcnt(2)
	v_pk_mul_f32 v[20:21], v[20:21], v[86:87]
	v_pk_mul_f32 v[22:23], v[22:23], v[88:89]
	s_waitcnt lgkmcnt(1)
	v_pk_mul_f32 v[24:25], v[24:25], v[90:91]
	v_pk_mul_f32 v[26:27], v[26:27], v[92:93]
	s_waitcnt lgkmcnt(0)
	v_pk_mul_f32 v[28:29], v[28:29], v[82:83]
	v_pk_mul_f32 v[30:31], v[30:31], v[84:85]
	s_barrier
	s_cbranch_scc1 .LBB0_304

.LBB0_422:
	s_or_b64 exec, exec, s[36:37]
	s_waitcnt lgkmcnt(0)
	s_barrier
	v_mov_b32_e32 v232, v156
	v_ashrrev_i32_e32 v233, 31, v156
	v_lshl_add_u64 v[232:233], v[232:233], 0, s[46:47]
	v_lshlrev_b64 v[232:233], 8, v[232:233]
	v_lshl_add_u64 v[232:233], v[150:151], 0, v[232:233]
	global_load_dwordx4 v[216:219], v[232:233], off offset:192
	global_load_dwordx4 v[220:223], v[232:233], off offset:128
	global_load_dwordx4 v[224:227], v[232:233], off offset:64
	global_load_dwordx4 v[228:231], v[232:233], off
	ds_read_b128 v[0:3], v167
	ds_read_b128 v[4:7], v167 offset:416
	ds_read_b128 v[8:11], v167 offset:448
	v_add_u32_e32 v157, v170, v179
	s_add_u32 s52, s52, 0x4000
	s_waitcnt lgkmcnt(2)
	v_pk_mul_f32 v[48:49], v[108:109], v[0:1]
	v_pk_mul_f32 v[50:51], v[114:115], v[2:3]
	ds_read_b128 v[0:3], v167 offset:32
	ds_read_b128 v[12:15], v167 offset:480
	v_cvt_pk_bf16_f32 v64, v48, v49
	v_cvt_pk_bf16_f32 v65, v50, v51
	s_waitcnt lgkmcnt(3)
	v_pk_mul_f32 v[4:5], v[144:145], v[4:5]
	s_waitcnt lgkmcnt(1)
	v_pk_mul_f32 v[52:53], v[52:53], v[0:1]
	v_pk_mul_f32 v[54:55], v[54:55], v[2:3]
	ds_read_b128 v[0:3], v167 offset:64
	v_cvt_pk_bf16_f32 v66, v52, v53
	v_cvt_pk_bf16_f32 v67, v54, v55
	v_pk_mul_f32 v[6:7], v[138:139], v[6:7]
	v_pk_mul_f32 v[8:9], v[146:147], v[8:9]
	s_waitcnt lgkmcnt(0)
	v_pk_mul_f32 v[56:57], v[56:57], v[0:1]
	v_pk_mul_f32 v[58:59], v[58:59], v[2:3]
	ds_read_b128 v[0:3], v167 offset:96
	v_pk_mul_f32 v[10:11], v[140:141], v[10:11]
	v_pk_mul_f32 v[12:13], v[148:149], v[12:13]
	v_pk_mul_f32 v[14:15], v[142:143], v[14:15]
	s_addc_u32 s53, s53, 0
	s_waitcnt lgkmcnt(0)
	v_pk_mul_f32 v[60:61], v[60:61], v[0:1]
	v_pk_mul_f32 v[62:63], v[62:63], v[2:3]
	ds_read_b128 v[0:3], v167 offset:128
	s_cmp_eq_u32 s52, 0x20000
	s_waitcnt lgkmcnt(0)
	v_pk_mul_f32 v[32:33], v[100:101], v[0:1]
	v_pk_mul_f32 v[34:35], v[96:97], v[2:3]
	ds_read_b128 v[0:3], v167 offset:160
	v_cvt_pk_bf16_f32 v100, v56, v57
	v_cvt_pk_bf16_f32 v101, v58, v59
	s_waitcnt lgkmcnt(0)
	v_pk_mul_f32 v[36:37], v[110:111], v[0:1]
	v_pk_mul_f32 v[38:39], v[102:103], v[2:3]
	ds_read_b128 v[0:3], v167 offset:192
	v_cvt_pk_bf16_f32 v102, v60, v61
	v_cvt_pk_bf16_f32 v103, v62, v63
	s_waitcnt lgkmcnt(0)
	v_pk_mul_f32 v[40:41], v[104:105], v[0:1]
	v_pk_mul_f32 v[42:43], v[98:99], v[2:3]
	ds_read_b128 v[0:3], v167 offset:224
	v_add_u32_e32 v104, 0x2000, v180
	s_waitcnt lgkmcnt(0)
	v_pk_mul_f32 v[44:45], v[116:117], v[0:1]
	v_pk_mul_f32 v[46:47], v[106:107], v[2:3]
	ds_read_b128 v[0:3], v167 offset:256
	s_waitcnt lgkmcnt(0)
	v_pk_mul_f32 v[16:17], v[122:123], v[0:1]
	v_pk_mul_f32 v[18:19], v[118:119], v[2:3]
	ds_read_b128 v[0:3], v167 offset:288
	s_waitcnt lgkmcnt(0)
	v_pk_mul_f32 v[20:21], v[130:131], v[0:1]
	v_pk_mul_f32 v[22:23], v[124:125], v[2:3]
	ds_read_b128 v[0:3], v167 offset:320
	s_waitcnt lgkmcnt(0)
	v_pk_mul_f32 v[24:25], v[126:127], v[0:1]
	v_pk_mul_f32 v[26:27], v[120:121], v[2:3]
	ds_read_b128 v[0:3], v167 offset:352
	s_waitcnt lgkmcnt(0)
	v_pk_mul_f32 v[28:29], v[132:133], v[0:1]
	v_pk_mul_f32 v[30:31], v[128:129], v[2:3]
	ds_read_b128 v[0:3], v167 offset:384
	ds_read2_b64 v[68:71], v180 offset1:2
	ds_read2_b64 v[96:99], v180 offset0:4 offset1:6
	s_waitcnt lgkmcnt(1)
	s_setprio 1
	v_mfma_f32_32x32x16_bf16 v[80:95], v[64:67], v[68:71], 0
	ds_read2_b64 v[68:71], v104 offset0:64 offset1:66
	v_mul_f32_e64 v0, v136, v0
	v_mul_f32_e64 v1, v137, v1
	v_mul_f32_e64 v2, v134, v2
	v_mul_f32_e64 v3, v135, v3
	s_waitcnt lgkmcnt(0)
	v_mfma_f32_32x32x16_bf16 v[64:79], v[64:67], v[68:71], 0
	v_mfma_f32_32x32x16_bf16 v[80:95], v[100:103], v[96:99], v[80:95]
	ds_read2_b64 v[96:99], v104 offset0:68 offset1:70
	s_waitcnt lgkmcnt(0)
	v_mfma_f32_32x32x16_bf16 v[64:79], v[100:103], v[96:99], v[64:79]
	v_cvt_pk_bf16_f32 v96, v32, v33
	v_cvt_pk_bf16_f32 v97, v34, v35
	v_cvt_pk_bf16_f32 v98, v36, v37
	v_cvt_pk_bf16_f32 v99, v38, v39
	ds_read2_b64 v[100:103], v180 offset0:8 offset1:10
	s_waitcnt lgkmcnt(0)
	v_mfma_f32_32x32x16_bf16 v[80:95], v[96:99], v[100:103], v[80:95]
	ds_read2_b64 v[100:103], v104 offset0:72 offset1:74
	s_waitcnt lgkmcnt(0)
	v_mfma_f32_32x32x16_bf16 v[64:79], v[96:99], v[100:103], v[64:79]
	v_cvt_pk_bf16_f32 v96, v40, v41
	v_cvt_pk_bf16_f32 v97, v42, v43
	v_cvt_pk_bf16_f32 v98, v44, v45
	v_cvt_pk_bf16_f32 v99, v46, v47
	ds_read2_b64 v[100:103], v180 offset0:12 offset1:14
	s_waitcnt lgkmcnt(0)
	v_mfma_f32_32x32x16_bf16 v[80:95], v[96:99], v[100:103], v[80:95]
	ds_read2_b64 v[100:103], v104 offset0:76 offset1:78
	s_waitcnt lgkmcnt(0)
	v_mfma_f32_32x32x16_bf16 v[64:79], v[96:99], v[100:103], v[64:79]
	v_cvt_pk_bf16_f32 v96, v16, v17
	v_cvt_pk_bf16_f32 v97, v18, v19
	v_cvt_pk_bf16_f32 v98, v20, v21
	v_cvt_pk_bf16_f32 v99, v22, v23
	ds_read2_b64 v[100:103], v180 offset0:16 offset1:18
	s_waitcnt lgkmcnt(0)
	v_mfma_f32_32x32x16_bf16 v[80:95], v[96:99], v[100:103], v[80:95]
	ds_read2_b64 v[100:103], v104 offset0:80 offset1:82
	s_waitcnt lgkmcnt(0)
	v_mfma_f32_32x32x16_bf16 v[64:79], v[96:99], v[100:103], v[64:79]
	v_cvt_pk_bf16_f32 v96, v24, v25
	v_cvt_pk_bf16_f32 v97, v26, v27
	v_cvt_pk_bf16_f32 v98, v28, v29
	v_cvt_pk_bf16_f32 v99, v30, v31
	ds_read2_b64 v[100:103], v180 offset0:20 offset1:22
	s_waitcnt lgkmcnt(0)
	v_mfma_f32_32x32x16_bf16 v[80:95], v[96:99], v[100:103], v[80:95]
	ds_read2_b64 v[100:103], v104 offset0:84 offset1:86
	s_waitcnt lgkmcnt(0)
	v_mfma_f32_32x32x16_bf16 v[64:79], v[96:99], v[100:103], v[64:79]
	v_cvt_pk_bf16_f32 v96, v0, v1
	v_cvt_pk_bf16_f32 v97, v2, v3
	v_cvt_pk_bf16_f32 v98, v4, v5
	v_cvt_pk_bf16_f32 v99, v6, v7
	ds_read2_b64 v[100:103], v180 offset0:24 offset1:26
	s_waitcnt lgkmcnt(0)
	v_mfma_f32_32x32x16_bf16 v[80:95], v[96:99], v[100:103], v[80:95]
	ds_read2_b64 v[100:103], v104 offset0:88 offset1:90
	s_waitcnt lgkmcnt(0)
	v_mfma_f32_32x32x16_bf16 v[64:79], v[96:99], v[100:103], v[64:79]
	v_cvt_pk_bf16_f32 v96, v8, v9
	v_cvt_pk_bf16_f32 v97, v10, v11
	v_cvt_pk_bf16_f32 v98, v12, v13
	v_cvt_pk_bf16_f32 v99, v14, v15
	ds_read2_b64 v[100:103], v180 offset0:28 offset1:30
	s_waitcnt lgkmcnt(0)
	v_mfma_f32_32x32x16_bf16 v[80:95], v[96:99], v[100:103], v[80:95]
	ds_read2_b64 v[100:103], v104 offset0:92 offset1:94
	s_waitcnt lgkmcnt(0)
	v_mfma_f32_32x32x16_bf16 v[64:79], v[96:99], v[100:103], v[64:79]
	ds_read_b128 v[114:117], v157 offset:17408
	ds_read_b128 v[96:99], v157
	ds_read_b128 v[118:121], v157 offset:32
	ds_read_b128 v[122:125], v157 offset:17440
	s_waitcnt lgkmcnt(2)
	v_mfma_f32_32x32x16_bf16 v[96:111], v[114:117], v[96:99], 0
	s_waitcnt lgkmcnt(0)
	v_mfma_f32_32x32x16_bf16 v[96:111], v[122:125], v[118:121], v[96:111]
	ds_read_b128 v[118:121], v157 offset:17472
	ds_read_b128 v[126:129], v157 offset:64
	s_waitcnt lgkmcnt(0)
	v_mfma_f32_32x32x16_bf16 v[96:111], v[118:121], v[126:129], v[96:111]
	ds_read_b128 v[126:129], v157 offset:17504
	ds_read_b128 v[130:133], v157 offset:96
	s_waitcnt lgkmcnt(0)
	v_mfma_f32_32x32x16_bf16 v[96:111], v[126:129], v[130:133], v[96:111]
	ds_read_b128 v[130:133], v157 offset:17536
	ds_read_b128 v[134:137], v157 offset:128
	s_waitcnt lgkmcnt(0)
	v_mfma_f32_32x32x16_bf16 v[96:111], v[130:133], v[134:137], v[96:111]
	ds_read_b128 v[134:137], v157 offset:17568
	ds_read_b128 v[138:141], v157 offset:160
	s_waitcnt lgkmcnt(0)
	v_mfma_f32_32x32x16_bf16 v[96:111], v[134:137], v[138:141], v[96:111]
	ds_read_b128 v[138:141], v157 offset:17600
	ds_read_b128 v[142:145], v157 offset:192
	s_waitcnt lgkmcnt(0)
	v_mfma_f32_32x32x16_bf16 v[96:111], v[138:141], v[142:145], v[96:111]
	ds_read_b128 v[142:145], v157 offset:17632
	ds_read_b128 v[146:149], v157 offset:224
	s_waitcnt lgkmcnt(0)
	v_mfma_f32_32x32x16_bf16 v[96:111], v[142:145], v[146:149], v[96:111]
	s_setprio 0
	s_nop 11
	v_cndmask_b32_e64 v146, v96, 0, s[34:35]
	v_cndmask_b32_e64 v96, v146, v96, s[30:31]
	v_cndmask_b32_e64 v97, 0, v97, s[30:31]
	v_cndmask_b32_e64 v98, v98, 0, s[28:29]
	v_cndmask_b32_e64 v99, v99, 0, s[26:27]
	v_cndmask_b32_e64 v100, v100, 0, s[24:25]
	v_cndmask_b32_e64 v101, v101, 0, s[22:23]
	v_cvt_pk_bf16_f32 v96, v96, v97
	v_cvt_pk_bf16_f32 v97, v98, v99
	v_cvt_pk_bf16_f32 v98, v100, v101
	v_add_u32_e32 v100, v171, v168
	v_add_u32_e32 v183, 0xd000, v100
	ds_read2_b64 v[146:149], v183 offset1:2
	ds_read2_b64 v[184:187], v183 offset0:4 offset1:6
	v_cndmask_b32_e64 v102, v102, 0, s[20:21]
	v_cndmask_b32_e64 v103, v103, 0, s[18:19]
	v_cvt_pk_bf16_f32 v99, v102, v103
	ds_read_b128 v[188:191], v157 offset:8704
	v_cndmask_b32_e64 v104, v104, 0, s[16:17]
	s_waitcnt lgkmcnt(2)
	v_mfma_f32_32x32x16_bf16 v[80:95], v[146:149], v[96:99], v[80:95]
	v_cndmask_b32_e64 v105, v105, 0, s[14:15]
	v_cndmask_b32_e64 v106, v106, 0, s[12:13]
	v_cndmask_b32_e64 v107, v107, 0, s[10:11]
	v_cndmask_b32_e64 v108, v108, 0, s[8:9]
	v_cndmask_b32_e64 v109, v109, 0, s[6:7]
	v_cndmask_b32_e64 v110, v110, 0, s[4:5]
	v_cndmask_b32_e64 v111, v111, 0, s[2:3]
	v_cvt_pk_bf16_f32 v96, v104, v105
	v_cvt_pk_bf16_f32 v97, v106, v107
	v_cvt_pk_bf16_f32 v98, v108, v109
	v_cvt_pk_bf16_f32 v99, v110, v111
	s_waitcnt lgkmcnt(1)
	s_nop 0
	s_setprio 1
	v_mfma_f32_32x32x16_bf16 v[80:95], v[184:187], v[96:99], v[80:95]
	s_waitcnt lgkmcnt(0)
	v_mfma_f32_32x32x16_bf16 v[96:111], v[114:117], v[188:191], 0
	ds_read_b128 v[114:117], v157 offset:8736
	s_waitcnt lgkmcnt(0)
	v_mfma_f32_32x32x16_bf16 v[96:111], v[122:125], v[114:117], v[96:111]
	ds_read_b128 v[122:125], v157 offset:8768
	s_waitcnt lgkmcnt(0)
	v_mfma_f32_32x32x16_bf16 v[96:111], v[118:121], v[122:125], v[96:111]
	ds_read_b128 v[118:121], v157 offset:8800
	s_waitcnt lgkmcnt(0)
	v_mfma_f32_32x32x16_bf16 v[96:111], v[126:129], v[118:121], v[96:111]
	ds_read_b128 v[126:129], v157 offset:8832
	s_waitcnt lgkmcnt(0)
	v_mfma_f32_32x32x16_bf16 v[96:111], v[130:133], v[126:129], v[96:111]
	ds_read_b128 v[130:133], v157 offset:8864
	s_waitcnt lgkmcnt(0)
	v_mfma_f32_32x32x16_bf16 v[96:111], v[134:137], v[130:133], v[96:111]
	ds_read_b128 v[134:137], v157 offset:8896
	s_waitcnt lgkmcnt(0)
	v_mfma_f32_32x32x16_bf16 v[96:111], v[138:141], v[134:137], v[96:111]
	ds_read_b128 v[138:141], v157 offset:8928
	s_waitcnt lgkmcnt(0)
	v_mfma_f32_32x32x16_bf16 v[96:111], v[142:145], v[138:141], v[96:111]
	ds_read_b128 v[142:145], v157 offset:26144
	s_nop 10
	v_cvt_pk_bf16_f32 v96, v96, v97
	v_cvt_pk_bf16_f32 v97, v98, v99
	v_cvt_pk_bf16_f32 v98, v100, v101
	v_cvt_pk_bf16_f32 v99, v102, v103
	s_nop 1
	v_mfma_f32_32x32x16_bf16 v[64:79], v[146:149], v[96:99], v[64:79]
	v_cvt_pk_bf16_f32 v96, v104, v105
	v_cvt_pk_bf16_f32 v97, v106, v107
	v_cvt_pk_bf16_f32 v98, v108, v109
	v_cvt_pk_bf16_f32 v99, v110, v111
	s_nop 1
	v_mfma_f32_32x32x16_bf16 v[64:79], v[184:187], v[96:99], v[64:79]
	ds_read_b128 v[96:99], v157 offset:26112
	s_waitcnt lgkmcnt(0)
	v_mfma_f32_32x32x16_bf16 v[96:111], v[96:99], v[188:191], 0
	v_mfma_f32_32x32x16_bf16 v[96:111], v[142:145], v[114:117], v[96:111]
	ds_read_b128 v[114:117], v157 offset:26176
	s_waitcnt lgkmcnt(0)
	v_mfma_f32_32x32x16_bf16 v[96:111], v[114:117], v[122:125], v[96:111]
	ds_read_b128 v[114:117], v157 offset:26208
	s_waitcnt lgkmcnt(0)
	v_mfma_f32_32x32x16_bf16 v[96:111], v[114:117], v[118:121], v[96:111]
	ds_read_b128 v[114:117], v157 offset:26240
	s_waitcnt lgkmcnt(0)
	v_mfma_f32_32x32x16_bf16 v[96:111], v[114:117], v[126:129], v[96:111]
	ds_read_b128 v[114:117], v157 offset:26272
	s_waitcnt lgkmcnt(0)
	v_mfma_f32_32x32x16_bf16 v[96:111], v[114:117], v[130:133], v[96:111]
	ds_read_b128 v[114:117], v157 offset:26304
	s_waitcnt lgkmcnt(0)
	v_mfma_f32_32x32x16_bf16 v[96:111], v[114:117], v[134:137], v[96:111]
	ds_read_b128 v[114:117], v157 offset:26336
	v_ashrrev_i32_e32 v157, 31, v156
	s_waitcnt lgkmcnt(0)
	v_mfma_f32_32x32x16_bf16 v[96:111], v[114:117], v[138:141], v[96:111]
	s_setprio 0
	s_nop 11
	v_cndmask_b32_e64 v114, v96, 0, s[34:35]
	v_cndmask_b32_e64 v96, v114, v96, s[30:31]
	v_cndmask_b32_e64 v97, 0, v97, s[30:31]
	v_cndmask_b32_e64 v98, v98, 0, s[28:29]
	v_cndmask_b32_e64 v99, v99, 0, s[26:27]
	v_cndmask_b32_e64 v100, v100, 0, s[24:25]
	v_cndmask_b32_e64 v101, v101, 0, s[22:23]
	v_cndmask_b32_e64 v102, v102, 0, s[20:21]
	v_cndmask_b32_e64 v103, v103, 0, s[18:19]
	v_cvt_pk_bf16_f32 v96, v96, v97
	v_cvt_pk_bf16_f32 v97, v98, v99
	v_cvt_pk_bf16_f32 v98, v100, v101
	v_cvt_pk_bf16_f32 v99, v102, v103
	ds_read2_b64 v[100:103], v183 offset0:8 offset1:10
	v_cndmask_b32_e64 v104, v104, 0, s[16:17]
	s_waitcnt lgkmcnt(0)
	v_mfma_f32_32x32x16_bf16 v[64:79], v[100:103], v[96:99], v[64:79]
	ds_read2_b64 v[100:103], v183 offset0:12 offset1:14
	v_cndmask_b32_e64 v105, v105, 0, s[14:15]
	v_cndmask_b32_e64 v106, v106, 0, s[12:13]
	v_cndmask_b32_e64 v107, v107, 0, s[10:11]
	v_cndmask_b32_e64 v108, v108, 0, s[8:9]
	v_cndmask_b32_e64 v109, v109, 0, s[6:7]
	v_cndmask_b32_e64 v110, v110, 0, s[4:5]
	v_cndmask_b32_e64 v111, v111, 0, s[2:3]
	v_cvt_pk_bf16_f32 v96, v104, v105
	v_cvt_pk_bf16_f32 v97, v106, v107
	v_cvt_pk_bf16_f32 v98, v108, v109
	v_cvt_pk_bf16_f32 v99, v110, v111
	v_add_u32_e32 v108, v171, v169
	s_waitcnt lgkmcnt(0)
	s_setprio 1
	v_mfma_f32_32x32x16_bf16 v[64:79], v[100:103], v[96:99], v[64:79]
	ds_read_b128 v[96:99], v108 offset:53248
	ds_read_b128 v[100:103], v108 offset:53280
	ds_read_b128 v[104:107], v108 offset:53312
	ds_read_b128 v[108:111], v108 offset:53344
	ds_read_b128 v[114:117], v181 offset:34816
	ds_read_b128 v[118:121], v181 offset:34848
	s_waitcnt lgkmcnt(1)
	v_mfma_f32_32x32x16_bf16 v[48:63], v[114:117], v[96:99], v[48:63]
	ds_read_b128 v[114:117], v181 offset:34880
	s_waitcnt lgkmcnt(1)
	v_mfma_f32_32x32x16_bf16 v[48:63], v[118:121], v[100:103], v[48:63]
	s_waitcnt lgkmcnt(0)
	v_mfma_f32_32x32x16_bf16 v[48:63], v[114:117], v[104:107], v[48:63]
	ds_read_b128 v[114:117], v181 offset:34912
	s_waitcnt lgkmcnt(0)
	v_mfma_f32_32x32x16_bf16 v[48:63], v[114:117], v[108:111], v[48:63]
	ds_read_b128 v[114:117], v181 offset:39424
	s_waitcnt lgkmcnt(0)
	v_mfma_f32_32x32x16_bf16 v[32:47], v[114:117], v[96:99], v[32:47]
	ds_read_b128 v[114:117], v181 offset:39456
	s_waitcnt lgkmcnt(0)
	v_mfma_f32_32x32x16_bf16 v[32:47], v[114:117], v[100:103], v[32:47]
	ds_read_b128 v[114:117], v181 offset:39488
	s_waitcnt lgkmcnt(0)
	v_mfma_f32_32x32x16_bf16 v[32:47], v[114:117], v[104:107], v[32:47]
	ds_read_b128 v[114:117], v181 offset:39520
	s_waitcnt lgkmcnt(0)
	v_mfma_f32_32x32x16_bf16 v[32:47], v[114:117], v[108:111], v[32:47]
	ds_read_b128 v[114:117], v181 offset:44032
	s_waitcnt lgkmcnt(0)
	v_mfma_f32_32x32x16_bf16 v[16:31], v[114:117], v[96:99], v[16:31]
	ds_read_b128 v[114:117], v181 offset:44064
	s_waitcnt lgkmcnt(0)
	v_mfma_f32_32x32x16_bf16 v[16:31], v[114:117], v[100:103], v[16:31]
	ds_read_b128 v[114:117], v181 offset:44096
	s_waitcnt lgkmcnt(0)
	v_mfma_f32_32x32x16_bf16 v[16:31], v[114:117], v[104:107], v[16:31]
	ds_read_b128 v[114:117], v181 offset:44128
	s_waitcnt lgkmcnt(0)
	v_mfma_f32_32x32x16_bf16 v[16:31], v[114:117], v[108:111], v[16:31]
	ds_read_b128 v[114:117], v181 offset:48640
	s_waitcnt lgkmcnt(0)
	v_mfma_f32_32x32x16_bf16 v[0:15], v[114:117], v[96:99], v[0:15]
	ds_read_b128 v[96:99], v181 offset:48672
	s_waitcnt lgkmcnt(0)
	v_mfma_f32_32x32x16_bf16 v[0:15], v[96:99], v[100:103], v[0:15]
	ds_read_b128 v[96:99], v181 offset:48704
	s_waitcnt lgkmcnt(0)
	v_mfma_f32_32x32x16_bf16 v[0:15], v[96:99], v[104:107], v[0:15]
	ds_read_b128 v[96:99], v181 offset:48736
	s_waitcnt lgkmcnt(0)
	v_mfma_f32_32x32x16_bf16 v[0:15], v[96:99], v[108:111], v[0:15]
	s_setprio 0
	ds_read_b128 v[96:99], v172
	ds_read_b128 v[100:103], v172 offset:32
	s_waitcnt lgkmcnt(1)
	v_mul_f32_e64 v108, v48, v96
	v_mul_f32_e64 v109, v49, v97
	v_pk_mul_f32 v[114:115], v[50:51], v[98:99]
	ds_read_b128 v[48:51], v172 offset:64
	s_waitcnt lgkmcnt(1)
	v_pk_mul_f32 v[52:53], v[52:53], v[100:101]
	v_pk_mul_f32 v[54:55], v[54:55], v[102:103]
	s_waitcnt lgkmcnt(0)
	v_pk_mul_f32 v[56:57], v[56:57], v[48:49]
	v_pk_mul_f32 v[58:59], v[58:59], v[50:51]
	ds_read_b128 v[48:51], v172 offset:96
	s_waitcnt lgkmcnt(0)
	v_pk_mul_f32 v[60:61], v[60:61], v[48:49]
	v_pk_mul_f32 v[62:63], v[62:63], v[50:51]
	ds_read_b128 v[48:51], v172 offset:128
	s_waitcnt lgkmcnt(0)
	v_pk_mul_f32 v[100:101], v[32:33], v[48:49]
	v_pk_mul_f32 v[96:97], v[34:35], v[50:51]
	ds_read_b128 v[32:35], v172 offset:160
	s_waitcnt lgkmcnt(0)
	v_pk_mul_f32 v[110:111], v[36:37], v[32:33]
	v_pk_mul_f32 v[102:103], v[38:39], v[34:35]
	ds_read_b128 v[32:35], v172 offset:192
	s_waitcnt lgkmcnt(0)
	v_pk_mul_f32 v[104:105], v[40:41], v[32:33]
	v_pk_mul_f32 v[98:99], v[42:43], v[34:35]
	ds_read_b128 v[32:35], v172 offset:224
	s_waitcnt lgkmcnt(0)
	v_pk_mul_f32 v[116:117], v[44:45], v[32:33]
	v_pk_mul_f32 v[106:107], v[46:47], v[34:35]
	ds_read_b128 v[32:35], v172 offset:256
	s_waitcnt lgkmcnt(0)
	v_pk_mul_f32 v[122:123], v[16:17], v[32:33]
	v_pk_mul_f32 v[118:119], v[18:19], v[34:35]
	ds_read_b128 v[16:19], v172 offset:288
	s_waitcnt lgkmcnt(0)
	v_pk_mul_f32 v[130:131], v[20:21], v[16:17]
	v_pk_mul_f32 v[124:125], v[22:23], v[18:19]
	ds_read_b128 v[16:19], v172 offset:320
	s_waitcnt lgkmcnt(0)
	v_pk_mul_f32 v[126:127], v[24:25], v[16:17]
	v_pk_mul_f32 v[120:121], v[26:27], v[18:19]
	ds_read_b128 v[16:19], v172 offset:352
	s_waitcnt lgkmcnt(0)
	v_pk_mul_f32 v[132:133], v[28:29], v[16:17]
	v_pk_mul_f32 v[128:129], v[30:31], v[18:19]
	ds_read_b128 v[16:19], v172 offset:384
	v_lshlrev_b64 v[30:31], 12, v[156:157]
	s_waitcnt lgkmcnt(0)
	v_pk_mul_f32 v[136:137], v[0:1], v[16:17]
	v_pk_mul_f32 v[134:135], v[2:3], v[18:19]
	ds_read_b128 v[0:3], v172 offset:416
	s_waitcnt lgkmcnt(0)
	v_pk_mul_f32 v[144:145], v[4:5], v[0:1]
	v_pk_mul_f32 v[138:139], v[6:7], v[2:3]
	ds_read_b128 v[0:3], v172 offset:448
	s_waitcnt lgkmcnt(0)
	v_pk_mul_f32 v[146:147], v[8:9], v[0:1]
	v_pk_mul_f32 v[140:141], v[10:11], v[2:3]
	ds_read_b128 v[0:3], v172 offset:480
	s_waitcnt lgkmcnt(0)
	s_barrier
	ds_write_b128 v182, v[80:83]
	ds_write_b128 v182, v[84:87] offset:32
	ds_write_b128 v182, v[88:91] offset:64
	ds_write_b128 v182, v[92:95] offset:96
	ds_write_b128 v182, v[64:67] offset:16896
	ds_write_b128 v182, v[68:71] offset:16928
	ds_write_b128 v182, v[72:75] offset:16960
	ds_write_b128 v182, v[76:79] offset:16992
	v_pk_mul_f32 v[148:149], v[12:13], v[0:1]
	v_pk_mul_f32 v[142:143], v[14:15], v[2:3]
	s_waitcnt lgkmcnt(0)
	s_barrier
	ds_read_b128 v[16:19], v173 offset:256
	ds_read_b128 v[12:15], v173 offset:272
	v_lshl_add_u64 v[64:65], v[152:153], 0, v[30:31]
	s_waitcnt lgkmcnt(1)
	v_pk_mul_f32 v[4:5], v[16:17], v[16:17]
	s_waitcnt lgkmcnt(0)
	v_pk_mul_f32 v[6:7], v[12:13], v[12:13]
	v_pk_mul_f32 v[0:1], v[18:19], v[18:19]
	v_pk_mul_f32 v[2:3], v[14:15], v[14:15]
	v_mov_b32_e32 v8, v4
	v_mov_b32_e32 v9, v6
	v_mov_b32_e32 v6, v5
	v_pk_add_f32 v[4:5], v[8:9], v[6:7]
	v_mov_b32_e32 v6, v0
	v_mov_b32_e32 v7, v2
	v_pk_add_f32 v[4:5], v[4:5], v[6:7]
	v_mov_b32_e32 v2, v1
	v_pk_add_f32 v[66:67], v[4:5], v[2:3]
	ds_read_b128 v[4:7], v173 offset:384
	ds_read_b128 v[0:3], v173 offset:400
	s_waitcnt lgkmcnt(1)
	v_pk_mul_f32 v[20:21], v[4:5], v[4:5]
	s_waitcnt lgkmcnt(0)
	v_pk_mul_f32 v[22:23], v[0:1], v[0:1]
	v_pk_mul_f32 v[8:9], v[6:7], v[6:7]
	v_pk_mul_f32 v[10:11], v[2:3], v[2:3]
	v_mov_b32_e32 v24, v20
	v_mov_b32_e32 v25, v22
	v_mov_b32_e32 v22, v21
	v_pk_add_f32 v[20:21], v[24:25], v[22:23]
	v_mov_b32_e32 v22, v8
	v_mov_b32_e32 v23, v10
	v_mov_b32_e32 v10, v9
	v_lshl_add_u64 v[8:9], v[156:157], 0, s[46:47]
	v_lshlrev_b64 v[8:9], 8, v[8:9]
	v_pk_add_f32 v[20:21], v[20:21], v[22:23]
	v_lshl_add_u64 v[28:29], v[150:151], 0, v[8:9]
	v_pk_add_f32 v[68:69], v[20:21], v[10:11]
	ds_read_b128 v[48:51], v173
	ds_read_b128 v[40:43], v173 offset:16
	ds_read_b128 v[32:35], v173 offset:128
	ds_read_b128 v[28:31], v173 offset:144
	global_load_dwordx4 v[36:39], v[154:155], off offset:16
	global_load_dwordx4 v[44:47], v[154:155], off
	s_waitcnt lgkmcnt(3)
	v_mov_b32_e32 v84, v49
	s_waitcnt lgkmcnt(2)
	v_mov_b32_e32 v85, v41
	v_mov_b32_e32 v78, v48
	v_mov_b32_e32 v79, v40
	v_pk_mul_f32 v[84:85], v[84:85], v[84:85]
	s_waitcnt lgkmcnt(1)
	v_mov_b32_e32 v90, v33
	v_pk_fma_f32 v[78:79], v[78:79], v[78:79], v[84:85]
	s_waitcnt lgkmcnt(0)
	v_mov_b32_e32 v91, v29
	v_mov_b32_e32 v74, v51
	v_mov_b32_e32 v75, v43
	v_mov_b32_e32 v88, v32
	v_mov_b32_e32 v89, v28
	v_pk_mul_f32 v[90:91], v[90:91], v[90:91]
	v_mov_b32_e32 v86, v35
	v_pk_fma_f32 v[88:89], v[88:89], v[88:89], v[90:91]
	v_mov_b32_e32 v87, v31
	v_add_u32_e32 v156, 64, v156
	s_waitcnt vmcnt(2)
	v_lshlrev_b32_e32 v80, 16, v229
	v_and_b32_e32 v81, 0xffff0000, v229
	v_lshlrev_b32_e32 v82, 16, v228
	v_and_b32_e32 v83, 0xffff0000, v228
	v_mov_b32_e32 v70, v50
	v_mov_b32_e32 v71, v42
	v_pk_fma_f32 v[70:71], v[70:71], v[70:71], v[78:79]
	v_lshlrev_b32_e32 v76, 16, v230
	v_and_b32_e32 v77, 0xffff0000, v230
	v_pk_fma_f32 v[84:85], v[74:75], v[74:75], v[70:71]
	v_lshlrev_b32_e32 v78, 16, v231
	v_and_b32_e32 v79, 0xffff0000, v231
	v_lshlrev_b32_e32 v72, 16, v225
	v_and_b32_e32 v73, 0xffff0000, v225
	v_lshlrev_b32_e32 v74, 16, v224
	v_and_b32_e32 v75, 0xffff0000, v224
	v_mov_b32_e32 v24, v34
	v_mov_b32_e32 v25, v30
	v_pk_fma_f32 v[24:25], v[24:25], v[24:25], v[88:89]
	v_lshlrev_b32_e32 v70, 16, v226
	v_and_b32_e32 v71, 0xffff0000, v226
	v_pk_fma_f32 v[24:25], v[86:87], v[86:87], v[24:25]
	v_add_f32_e32 v26, v84, v85
	v_add_f32_e32 v24, v26, v24
	v_add_f32_e32 v24, v24, v25
	v_add_f32_e32 v24, v24, v66
	v_add_f32_e32 v24, v24, v67
	v_add_f32_e32 v24, v24, v68
	v_add_f32_e32 v24, v24, v69
	ds_bpermute_b32 v25, v174, v24
	v_lshlrev_b32_e32 v26, 16, v227
	v_and_b32_e32 v27, 0xffff0000, v227
	s_waitcnt lgkmcnt(0)
	v_add_f32_e32 v24, v24, v25
	ds_bpermute_b32 v25, v175, v24
	s_waitcnt lgkmcnt(0)
	v_add_f32_e32 v24, v24, v25
	v_fmamk_f32 v24, v24, 0x3c000000, v161
	v_cmp_gt_f32_e64 s[36:37], s70, v24
	v_mul_f32_e32 v25, 0x4b800000, v24
	s_nop 0
	v_cndmask_b32_e64 v24, v24, v25, s[36:37]
	v_rsq_f32_e32 v24, v24
	s_nop 0
	v_mul_f32_e32 v25, 0x45800000, v24
	v_cndmask_b32_e64 v24, v24, v25, s[36:37]
	v_pk_mul_f32 v[48:49], v[48:49], v[24:25] op_sel_hi:[1,0]
	v_pk_mul_f32 v[40:41], v[40:41], v[24:25] op_sel_hi:[1,0]
	s_waitcnt vmcnt(0)
	v_pk_mul_f32 v[44:45], v[44:45], v[48:49]
	v_pk_mul_f32 v[48:49], v[50:51], v[24:25] op_sel_hi:[1,0]
	v_pk_mul_f32 v[36:37], v[36:37], v[40:41]
	v_pk_mul_f32 v[46:47], v[46:47], v[48:49]
	v_pk_mul_f32 v[44:45], v[44:45], v[82:83]
	v_pk_mul_f32 v[46:47], v[46:47], v[80:81]
	v_pk_mul_f32 v[36:37], v[36:37], v[76:77]
	v_cvt_pk_bf16_f32 v44, v44, v45
	v_cvt_pk_bf16_f32 v45, v46, v47
	v_cvt_pk_bf16_f32 v46, v36, v37
	v_pk_mul_f32 v[36:37], v[42:43], v[24:25] op_sel_hi:[1,0]
	v_pk_mul_f32 v[32:33], v[32:33], v[24:25] op_sel_hi:[1,0]
	v_pk_mul_f32 v[36:37], v[36:37], v[38:39]
	v_pk_mul_f32 v[34:35], v[34:35], v[24:25] op_sel_hi:[1,0]
	v_pk_mul_f32 v[36:37], v[36:37], v[78:79]
	v_pk_mul_f32 v[28:29], v[28:29], v[24:25] op_sel_hi:[1,0]
	v_cvt_pk_bf16_f32 v47, v36, v37
	global_store_dwordx4 v[64:65], v[44:47], off
	global_load_dwordx4 v[36:39], v[154:155], off offset:144
	global_load_dwordx4 v[40:43], v[154:155], off offset:128
	v_pk_mul_f32 v[16:17], v[16:17], v[24:25] op_sel_hi:[1,0]
	v_pk_mul_f32 v[18:19], v[18:19], v[24:25] op_sel_hi:[1,0]
	v_pk_mul_f32 v[12:13], v[12:13], v[24:25] op_sel_hi:[1,0]
	v_pk_mul_f32 v[4:5], v[4:5], v[24:25] op_sel_hi:[1,0]
	v_pk_mul_f32 v[6:7], v[6:7], v[24:25] op_sel_hi:[1,0]
	v_pk_mul_f32 v[0:1], v[0:1], v[24:25] op_sel_hi:[1,0]
	s_waitcnt vmcnt(1)
	v_pk_mul_f32 v[28:29], v[28:29], v[36:37]
	s_waitcnt vmcnt(0)
	v_pk_mul_f32 v[32:33], v[32:33], v[40:41]
	v_pk_mul_f32 v[34:35], v[34:35], v[42:43]
	v_pk_mul_f32 v[32:33], v[32:33], v[74:75]
	v_pk_mul_f32 v[34:35], v[34:35], v[72:73]
	v_pk_mul_f32 v[28:29], v[28:29], v[70:71]
	v_cvt_pk_bf16_f32 v32, v32, v33
	v_cvt_pk_bf16_f32 v33, v34, v35
	v_cvt_pk_bf16_f32 v34, v28, v29
	v_pk_mul_f32 v[28:29], v[30:31], v[24:25] op_sel_hi:[1,0]
	s_nop 0
	v_pk_mul_f32 v[28:29], v[28:29], v[38:39]
	s_nop 0
	v_pk_mul_f32 v[26:27], v[28:29], v[26:27]
	s_nop 0
	v_cvt_pk_bf16_f32 v35, v26, v27
	global_store_dwordx4 v[64:65], v[32:35], off offset:64
	global_load_dwordx4 v[26:29], v[154:155], off offset:272
	s_nop 0
	global_load_dwordx4 v[30:33], v[154:155], off offset:256
	s_waitcnt vmcnt(1)
	v_pk_mul_f32 v[12:13], v[12:13], v[26:27]
	s_waitcnt vmcnt(0)
	v_pk_mul_f32 v[16:17], v[16:17], v[30:31]
	v_lshlrev_b32_e32 v30, 16, v220
	v_and_b32_e32 v31, 0xffff0000, v220
	v_pk_mul_f32 v[18:19], v[18:19], v[32:33]
	v_lshlrev_b32_e32 v20, 16, v221
	v_and_b32_e32 v21, 0xffff0000, v221
	v_pk_mul_f32 v[16:17], v[16:17], v[30:31]
	v_pk_mul_f32 v[18:19], v[18:19], v[20:21]
	v_cvt_pk_bf16_f32 v16, v16, v17
	v_cvt_pk_bf16_f32 v17, v18, v19
	v_lshlrev_b32_e32 v18, 16, v222
	v_and_b32_e32 v19, 0xffff0000, v222
	v_pk_mul_f32 v[12:13], v[12:13], v[18:19]
	s_nop 0
	v_cvt_pk_bf16_f32 v18, v12, v13
	v_pk_mul_f32 v[12:13], v[14:15], v[24:25] op_sel_hi:[1,0]
	v_lshlrev_b32_e32 v14, 16, v223
	v_pk_mul_f32 v[12:13], v[12:13], v[28:29]
	v_and_b32_e32 v15, 0xffff0000, v223
	v_pk_mul_f32 v[12:13], v[12:13], v[14:15]
	s_nop 0
	v_cvt_pk_bf16_f32 v19, v12, v13
	global_store_dwordx4 v[64:65], v[16:19], off offset:128
	global_load_dwordx4 v[12:15], v[154:155], off offset:400
	s_nop 0
	global_load_dwordx4 v[16:19], v[154:155], off offset:384
	s_waitcnt vmcnt(1)
	v_pk_mul_f32 v[0:1], v[0:1], v[12:13]
	s_waitcnt vmcnt(0)
	v_pk_mul_f32 v[4:5], v[4:5], v[16:17]
	v_lshlrev_b32_e32 v16, 16, v216
	v_and_b32_e32 v17, 0xffff0000, v216
	v_pk_mul_f32 v[6:7], v[6:7], v[18:19]
	v_lshlrev_b32_e32 v8, 16, v217
	v_and_b32_e32 v9, 0xffff0000, v217
	v_pk_mul_f32 v[4:5], v[4:5], v[16:17]
	v_pk_mul_f32 v[6:7], v[6:7], v[8:9]
	v_cvt_pk_bf16_f32 v4, v4, v5
	v_cvt_pk_bf16_f32 v5, v6, v7
	v_lshlrev_b32_e32 v6, 16, v218
	v_and_b32_e32 v7, 0xffff0000, v218
	v_pk_mul_f32 v[0:1], v[0:1], v[6:7]
	s_nop 0
	v_cvt_pk_bf16_f32 v6, v0, v1
	v_pk_mul_f32 v[0:1], v[2:3], v[24:25] op_sel_hi:[1,0]
	v_lshlrev_b32_e32 v2, 16, v219
	v_pk_mul_f32 v[0:1], v[0:1], v[14:15]
	v_and_b32_e32 v3, 0xffff0000, v219
	v_pk_mul_f32 v[0:1], v[0:1], v[2:3]
	s_nop 0
	v_cvt_pk_bf16_f32 v7, v0, v1
	global_store_dwordx4 v[64:65], v[4:7], off offset:192
	s_cbranch_scc1 .LBB0_425
